# plus static s_setprio 1 for merge (3/4) loop waves 4-7
# baseline (speedup 1.0000x reference)
.LBB0_975:
	s_or_b64 exec, exec, s[0:1]
	v_readlane_b32 s0, v252, 6
	v_readlane_b32 s2, v254, 2
	v_readlane_b32 s3, v254, 3
	s_add_u32 s2, s0, s2
	v_readlane_b32 s0, v252, 7
	s_addc_u32 s3, s0, s3
	v_readlane_b32 s0, v252, 61
	s_add_u32 s70, s2, s0
	s_addc_u32 s71, s3, 0
	v_readlane_b32 s0, v252, 62
	s_add_u32 s74, s2, s0
	s_addc_u32 s75, s3, 0
	v_readlane_b32 s0, v252, 63
	s_add_u32 s82, s2, s0
	s_addc_u32 s83, s3, 0
	v_readlane_b32 s0, v253, 0
	s_add_u32 s90, s2, s0
	s_addc_u32 s91, s3, 0
	v_readlane_b32 s0, v253, 1
	s_add_u32 s16, s2, s0
	s_addc_u32 s17, s3, 0
	v_readlane_b32 s0, v253, 2
	s_add_u32 s46, s2, s0
	s_addc_u32 s47, s3, 0
	v_readlane_b32 s0, v253, 3
	s_add_u32 s42, s2, s0
	s_addc_u32 s43, s3, 0
	v_readlane_b32 s0, v253, 4
	s_add_u32 s4, s2, s0
	v_mov_b32_e32 v2, v182
	v_readlane_b32 s0, v253, 26
	s_addc_u32 s5, s3, 0
	s_barrier
	v_readlane_b32 s1, v253, 27
	v_readfirstlane_b32 s39, v2
	s_nop 0
	s_cmp_lt_u32 s39, 0x100
	s_cbranch_scc1 .Lm3_prio_skip
	s_setprio 1
.Lm3_prio_skip:
	s_and_saveexec_b64 s[2:3], s[0:1]
	s_cbranch_execz .LBB0_1007
	s_mov_b64 s[20:21], exec
	v_mbcnt_lo_u32_b32 v1, s20, 0
	v_mbcnt_hi_u32_b32 v1, s21, v1
	v_cmp_eq_u32_e32 vcc, 0, v1
	s_and_saveexec_b64 s[18:19], vcc
	s_cbranch_execz .LBB0_978
	s_bcnt1_i32_b64 s20, s[20:21]
	v_mov_b32_e32 v3, s20
	global_atomic_add v3, v0, v3, s[16:17] sc0

.LBB0_1083:
	s_setprio 0
	s_waitcnt vmcnt(0)
	s_cmp_lg_u32 s51, 0
	v_readlane_b32 s2, v253, 26
	s_cselect_b64 s[0:1], -1, 0
	v_readlane_b32 s3, v253, 27
	s_and_b64 s[4:5], s[2:3], s[0:1]
	s_waitcnt vmcnt(0) lgkmcnt(0)
	s_barrier
	s_and_saveexec_b64 s[0:1], s[4:5]
	s_movk_i32 s42, 0x277
	s_mov_b32 s43, 0x10000
	s_mov_b32 s44, 0x20000
	s_mov_b32 s45, 0x30000
	s_mov_b32 s46, 0x40000
	s_mov_b32 s47, 0x50000
	s_mov_b32 s49, 0x60000
	s_mov_b32 s50, 0x70000
	s_mov_b32 s52, 0x3ffffffc
	s_movk_i32 s53, 0x7c50
	s_mov_b64 s[70:71], 0x80
	s_cbranch_execz .LBB0_1086
	s_mov_b64 s[4:5], exec
	v_mbcnt_lo_u32_b32 v1, s4, 0
	buffer_wbl2 sc1
	s_waitcnt vmcnt(0)
	v_mbcnt_hi_u32_b32 v1, s5, v1
	v_cmp_eq_u32_e32 vcc, 0, v1
	s_and_b64 s[6:7], exec, vcc
	s_mov_b64 exec, s[6:7]
	s_cbranch_execz .LBB0_1086
	s_bcnt1_i32_b64 s4, s[4:5]
	s_mul_i32 s4, s51, s4
	v_mov_b32_e32 v1, s4
	global_atomic_add v0, v1, s[54:55] offset:1024
